# v84 + 39-instruction recurrence step (rec8) + SS rows added to the late-scan prefetch list
# speedup vs baseline: 1.0042x; 1.0042x over previous
.Lcv_noitem:
	s_sub_u32 s54, s12, 48
	s_cmp_lt_u32 s54, 11
	s_cbranch_scc0 .Lpf_skip
	s_lshl_b32 s54, s54, 10
	s_lshl_b32 s53, s8, 2
	s_add_i32 s53, s53, s11
	s_add_i32 s53, s53, -4
	s_add_i32 s54, s54, s53
	s_cmp_lt_u32 s54, 0x2b04
	s_cbranch_scc0 .Lpf_skip
	s_cmp_lt_u32 s54, 0x2080
	s_cbranch_scc0 .Lpf_win
	s_lshl_b32 s55, s54, 12
	s_add_u32 s56, s84, s55
	s_addc_u32 s57, s85, 0
	s_branch .Lpf_go
.Lpf_win:
	s_cmp_lt_u32 s54, 0x2a00
	s_cbranch_scc0 .Lpf_ss
	s_sub_u32 s55, s54, 0x2080
	s_lshl_b32 s55, s55, 12
	s_add_u32 s56, s86, 0x1780000
	s_addc_u32 s57, s87, 0
	s_add_u32 s56, s56, s55
	s_addc_u32 s57, s57, 0
	s_branch .Lpf_go
.Lpf_ss:
	s_sub_u32 s55, s54, 0x2a00
	s_lshl_b32 s55, s55, 12
	s_add_u32 s56, s86, 0x7780000
	s_addc_u32 s57, s87, 0
	s_add_u32 s56, s56, s55
	s_addc_u32 s57, s57, 0
